# MLA attention unit prologue: the four LDS-resident Q fragments loaded together (one wait) instead of a load/wait/ds_write ladder; on top of the epilogue de-serialisation bundle
# speedup vs baseline: 1.0090x; 1.0036x over previous
.LBB0_1093:
	s_mov_b64 s[8:9], s[0:1]
	v_mov_b32_e32 v12, v0
	s_load_dwordx2 s[8:9], s[8:9], 0xd8
	s_add_i32 s17, 0, 0x14000
	v_ashrrev_i32_e32 v2, 6, v12
	v_and_b32_e32 v161, 31, v12
	v_and_b32_e32 v4, 0x3fffffc0, v12
	v_lshlrev_b32_e32 v170, 5, v2
	v_bfe_u32 v169, v12, 5, 1
	v_lshl_add_u32 v54, v4, 2, s17
	v_or_b32_e32 v6, v170, v161
	v_mov_b64_e32 v[4:5], s[6:7]
	v_mad_i64_i32 v[4:5], s[6:7], v6, s84, v[4:5]
	v_lshlrev_b32_e32 v52, 4, v169
	v_mov_b32_e32 v53, v3
	v_lshl_add_u64 v[8:9], v[4:5], 0, v[52:53]
	global_load_dwordx4 v[128:131], v[8:9], off
	global_load_dwordx4 v[124:127], v[8:9], off offset:32
	global_load_dwordx4 v[120:123], v[8:9], off offset:64
	global_load_dwordx4 v[116:119], v[8:9], off offset:96
	global_load_dwordx4 v[112:115], v[8:9], off offset:128
	global_load_dwordx4 v[108:111], v[8:9], off offset:160
	global_load_dwordx4 v[104:107], v[8:9], off offset:192
	global_load_dwordx4 v[100:103], v[8:9], off offset:224
	global_load_dwordx4 v[4:7], v[8:9], off offset:256
	global_load_dwordx4 v[14:17], v[8:9], off offset:288
	global_load_dwordx4 v[18:21], v[8:9], off offset:320
	global_load_dwordx4 v[22:25], v[8:9], off offset:352
	v_and_b32_e32 v168, 63, v12
	s_add_i32 s6, 0, 0x16a00
	v_lshl_add_u32 v171, v2, 12, s6
	v_lshlrev_b32_e32 v2, 4, v168
	v_add_u32_e32 v173, v171, v2
	v_ashrrev_i32_e32 v13, 4, v12
	v_add_u32_e32 v28, 32, v13
	v_and_b32_e32 v2, 0xc0, v2
	v_ashrrev_i32_e32 v30, 3, v12
	v_lshlrev_b32_e32 v31, 7, v30
	s_cmp_lg_u32 0, -1
	s_cselect_b32 s6, 0, 0
	v_lshlrev_b32_e32 v64, 8, v161
	v_or_b32_e32 v68, 32, v52
	v_or_b32_e32 v69, 64, v52
	v_or_b32_e32 v70, 0x60, v52
	v_lshlrev_b32_e32 v71, 7, v161
	s_mov_b32 s17, s16
	s_mov_b32 s18, s16
	s_mov_b32 s19, s16
	s_mov_b32 s20, s16
	s_mov_b32 s21, s16
	s_mov_b32 s22, s16
	s_mov_b32 s23, s16
	s_mov_b32 s24, s16
	s_mov_b32 s25, s16
	s_mov_b32 s26, s16
	s_mov_b32 s27, s16
	s_mov_b32 s28, s16
	s_mov_b32 s29, s16
	s_mov_b32 s30, s16
	s_mov_b32 s31, s16
	v_lshl_add_u32 v175, v161, 2, v54
	v_add_u32_e32 v174, v54, v52
	s_mov_b32 s46, 2
	s_movk_i32 s47, 0xc0
	v_mov_b32_e32 v163, v3
	v_mov_b32_e32 v178, 0
	s_waitcnt vmcnt(0)
	ds_write_b128 v173, v[4:7]
	ds_write_b128 v173, v[14:17] offset:1024
	ds_write_b128 v173, v[18:21] offset:2048
	v_and_b32_e32 v8, 3, v13
	v_mov_b32_e32 v9, v3
	ds_write_b128 v173, v[22:25] offset:3072
	v_and_b32_e32 v6, 0xfffff0, v13
	v_lshlrev_b32_e32 v7, 1, v13
	v_lshlrev_b32_e32 v4, 3, v12
	v_and_or_b32 v6, v7, 8, v6
	v_and_b32_e32 v5, 0x78, v4
	v_lshrrev_b32_e32 v7, 1, v13
	v_lshrrev_b32_e32 v6, 1, v6
	v_bfe_u32 v4, v4, 5, 2
	v_or_b32_e32 v6, v6, v4
	v_and_or_b32 v7, v7, 4, v8
	v_lshlrev_b32_e32 v26, 1, v5
	v_lshlrev_b32_e32 v6, 9, v6
	v_lshlrev_b32_e32 v7, 6, v7
	v_and_b32_e32 v5, 48, v26
	v_or3_b32 v27, v6, v7, v5
	v_and_b32_e32 v6, 0xfffff0, v28
	v_lshlrev_b32_e32 v8, 1, v28
	v_and_or_b32 v6, v8, 8, v6
	v_lshrrev_b32_e32 v6, 1, v6
	v_or_b32_e32 v4, v6, v4
	v_lshlrev_b32_e32 v4, 9, v4
	v_or3_b32 v29, v4, v7, v5
	v_lshlrev_b32_e32 v4, 3, v168
	v_lshlrev_b32_e32 v5, 1, v12
	v_and_or_b32 v2, v4, 24, v2
	v_and_b32_e32 v5, 32, v5
	v_and_b32_e32 v4, 0x100, v4
	v_or3_b32 v53, v2, v5, v4
	v_lshlrev_b32_e32 v2, 4, v12
	v_and_b32_e32 v160, 0x70, v2
	v_lshl_or_b32 v2, v13, 11, v26
	global_load_dwordx4 v[14:17], v2, s[94:95]
	v_add_u32_e32 v162, 0x10000, v2
	global_load_dwordx4 v[18:21], v162, s[94:95]
	global_load_dwordx4 v[22:25], v2, s[14:15]
	global_load_dwordx4 v[4:7], v162, s[14:15]
	v_or_b32_e32 v8, v31, v160
	v_lshl_add_u64 v[164:165], s[4:5], 0, v[8:9]
	global_load_dwordx4 v[8:11], v8, s[4:5]
	v_add_u32_e32 v176, 0, v27
	s_waitcnt vmcnt(0)
	v_lshlrev_b32_e32 v13, 8, v13
	v_add_u32_e32 v177, 0, v29
	s_movk_i32 s4, 0x70
	v_bitop3_b32 v56, v68, v64, v160 bitop3:0xde
	v_add_u32_e32 v184, 0, v56
	v_bitop3_b32 v190, v52, v71, v160 bitop3:0xde
	v_bitop3_b32 v192, v68, v71, v160 bitop3:0xde
	v_bitop3_b32 v194, v69, v71, v160 bitop3:0xde
	v_bitop3_b32 v200, v70, v71, v160 bitop3:0xde
	v_add_u32_e32 v172, s6, v53
	v_lshl_add_u64 v[166:167], v[164:165], 0, s[50:51]
	s_waitcnt vmcnt(4)
	ds_write_b128 v176, v[14:17]
	v_and_b32_e32 v14, 0x70, v12
	v_bitop3_b32 v13, v26, v13, v14 bitop3:0xde
	v_add_u32_e32 v180, 0, v13
	v_lshlrev_b32_e32 v13, 8, v28
	v_bitop3_b32 v13, v26, v13, v14 bitop3:0xde
	v_add_u32_e32 v181, 0, v13
	s_waitcnt vmcnt(3)
	ds_write_b128 v177, v[18:21]
	s_waitcnt vmcnt(2)
	ds_write_b128 v180, v[22:25] offset:32768
	s_waitcnt vmcnt(1)
	ds_write_b128 v181, v[4:7] offset:32768
	v_xor_b32_e32 v4, v30, v12
	v_lshlrev_b32_e32 v4, 4, v4
	v_and_or_b32 v55, v4, s4, v31
	s_add_i32 s4, 0, 0x10000
	v_add_u32_e32 v4, s4, v55
	s_waitcnt vmcnt(0)
	ds_write_b128 v4, v[8:11]
	v_bitop3_b32 v4, v52, v64, v160 bitop3:0xde
	v_add_u32_e32 v182, 0, v4
	s_waitcnt lgkmcnt(0)
	s_barrier
	ds_read_b128 v[20:23], v182 offset:32768
	ds_read_b128 v[24:27], v182 offset:40960
	s_waitcnt lgkmcnt(1)
	v_mfma_f32_32x32x16_bf16 v[36:51], v[20:23], v[128:131], 0
	ds_read_b128 v[56:59], v184 offset:32768
	ds_read_b128 v[60:63], v184 offset:40960
	v_add_u32_e32 v191, s4, v190
	v_add_u32_e32 v193, s4, v192
	v_add_u32_e32 v195, s4, v194
	v_add_u32_e32 v201, s4, v200
	v_mov_b64_e32 v[4:5], s[16:17]
	v_mov_b64_e32 v[6:7], s[18:19]
	s_waitcnt lgkmcnt(2)
	v_mfma_f32_32x32x16_bf16 v[20:35], v[24:27], v[128:131], 0
	v_mov_b64_e32 v[8:9], s[20:21]
	v_mov_b64_e32 v[10:11], s[22:23]
	v_mov_b64_e32 v[12:13], s[24:25]
	v_mov_b64_e32 v[14:15], s[26:27]
	v_mov_b64_e32 v[16:17], s[28:29]
	v_mov_b64_e32 v[18:19], s[30:31]
	v_add_u32_e32 v203, 0, v55
	s_waitcnt lgkmcnt(1)
	v_mfma_f32_32x32x16_bf16 v[36:51], v[56:59], v[124:127], v[36:51]
	v_bitop3_b32 v56, v69, v64, v160 bitop3:0xde
	v_add_u32_e32 v186, 0, v56
	v_add_u32_e32 v204, 0x12000, v203
	s_waitcnt lgkmcnt(0)
	v_mfma_f32_32x32x16_bf16 v[20:35], v[60:63], v[124:127], v[20:35]
	ds_read_b128 v[56:59], v186 offset:32768
	ds_read_b128 v[60:63], v186 offset:40960
	s_waitcnt lgkmcnt(1)
	v_mfma_f32_32x32x16_bf16 v[36:51], v[56:59], v[120:123], v[36:51]
	v_bitop3_b32 v56, v70, v64, v160 bitop3:0xde
	v_add_u32_e32 v188, 0, v56
	s_waitcnt lgkmcnt(0)
	v_mfma_f32_32x32x16_bf16 v[20:35], v[60:63], v[120:123], v[20:35]
	ds_read_b128 v[56:59], v188 offset:32768
	ds_read_b128 v[60:63], v188 offset:40960
	s_waitcnt lgkmcnt(1)
	v_mfma_f32_32x32x16_bf16 v[36:51], v[56:59], v[116:119], v[36:51]
	v_or_b32_e32 v56, 0x80, v52
	v_bitop3_b32 v56, v56, v64, v160 bitop3:0xde
	v_add_u32_e32 v189, 0, v56
	s_waitcnt lgkmcnt(0)
	v_mfma_f32_32x32x16_bf16 v[20:35], v[60:63], v[116:119], v[20:35]
	ds_read_b128 v[56:59], v189 offset:32768
	ds_read_b128 v[60:63], v189 offset:40960
	s_waitcnt lgkmcnt(1)
	v_mfma_f32_32x32x16_bf16 v[36:51], v[56:59], v[112:115], v[36:51]
	v_or_b32_e32 v56, 0xa0, v52
	v_bitop3_b32 v56, v56, v64, v160 bitop3:0xde
	v_add_u32_e32 v187, 0, v56
	s_waitcnt lgkmcnt(0)
	v_mfma_f32_32x32x16_bf16 v[20:35], v[60:63], v[112:115], v[20:35]
	ds_read_b128 v[56:59], v187 offset:32768
	ds_read_b128 v[60:63], v187 offset:40960
	s_waitcnt lgkmcnt(1)
	v_mfma_f32_32x32x16_bf16 v[36:51], v[56:59], v[108:111], v[36:51]
	v_or_b32_e32 v56, 0xc0, v52
	v_bitop3_b32 v56, v56, v64, v160 bitop3:0xde
	v_add_u32_e32 v185, 0, v56
	s_waitcnt lgkmcnt(0)
	v_mfma_f32_32x32x16_bf16 v[20:35], v[60:63], v[108:111], v[20:35]
	ds_read_b128 v[56:59], v185 offset:32768
	ds_read_b128 v[60:63], v185 offset:40960
	s_waitcnt lgkmcnt(1)
	v_mfma_f32_32x32x16_bf16 v[36:51], v[56:59], v[104:107], v[36:51]
	v_or_b32_e32 v56, 0xe0, v52
	v_bitop3_b32 v56, v56, v64, v160 bitop3:0xde
	v_add_u32_e32 v183, 0, v56
	s_waitcnt lgkmcnt(0)
	v_mfma_f32_32x32x16_bf16 v[20:35], v[60:63], v[104:107], v[20:35]
	ds_read_b128 v[56:59], v183 offset:32768
	ds_read_b128 v[60:63], v183 offset:40960
	s_waitcnt lgkmcnt(1)
	v_mfma_f32_32x32x16_bf16 v[36:51], v[56:59], v[100:103], v[36:51]
	s_waitcnt lgkmcnt(0)
	v_mfma_f32_32x32x16_bf16 v[20:35], v[60:63], v[100:103], v[20:35]
	ds_read_b128 v[56:59], v191
	ds_read_b128 v[60:63], v191 offset:4096
	ds_read_b128 v[64:67], v173
	s_waitcnt lgkmcnt(0)
	v_mfma_f32_32x32x16_bf16 v[36:51], v[56:59], v[64:67], v[36:51]
	v_mfma_f32_32x32x16_bf16 v[20:35], v[60:63], v[64:67], v[20:35]
	ds_read_b128 v[56:59], v193
	ds_read_b128 v[60:63], v193 offset:4096
	ds_read_b128 v[64:67], v173 offset:1024
	s_waitcnt lgkmcnt(0)
	v_mfma_f32_32x32x16_bf16 v[36:51], v[56:59], v[64:67], v[36:51]
	v_mfma_f32_32x32x16_bf16 v[20:35], v[60:63], v[64:67], v[20:35]
	ds_read_b128 v[56:59], v195
	ds_read_b128 v[60:63], v195 offset:4096
	ds_read_b128 v[64:67], v173 offset:2048
	s_waitcnt lgkmcnt(0)
	v_mfma_f32_32x32x16_bf16 v[36:51], v[56:59], v[64:67], v[36:51]
	v_mfma_f32_32x32x16_bf16 v[20:35], v[60:63], v[64:67], v[20:35]
	ds_read_b128 v[56:59], v201
	ds_read_b128 v[60:63], v201 offset:4096
	ds_read_b128 v[64:67], v173 offset:3072
	s_waitcnt lgkmcnt(0)
	v_mfma_f32_32x32x16_bf16 v[36:51], v[56:59], v[64:67], v[36:51]
	v_mfma_f32_32x32x16_bf16 v[20:35], v[60:63], v[64:67], v[20:35]
	s_nop 10
	v_max_f32_e32 v56, v37, v37
	v_max_f32_e32 v57, v36, v36
	v_max_f32_e32 v56, v57, v56
	v_max3_f32 v56, v56, v38, v39
	v_max3_f32 v56, v56, v40, v41
	v_max3_f32 v56, v56, v42, v43
	v_max3_f32 v56, v56, v44, v45
	v_max3_f32 v56, v56, v46, v47
	v_max3_f32 v56, v56, v48, v49
	v_max3_f32 v56, v56, v50, v51
	v_max3_f32 v56, v56, v20, v21
	v_max3_f32 v56, v56, v22, v23
	v_max3_f32 v56, v56, v24, v25
	v_max3_f32 v56, v56, v26, v27
	v_max3_f32 v56, v56, v28, v29
	v_max3_f32 v56, v56, v30, v31
	v_max3_f32 v56, v56, v32, v33
	v_max3_f32 v56, v56, v34, v35
	v_mov_b32_e32 v57, v56
	s_nop 1
	v_permlane32_swap_b32_e32 v56, v57
	v_max_f32_e32 v57, v57, v57
	v_max_f32_e32 v56, v56, v56
	v_max_f32_e32 v56, v56, v57
	v_add_f32_e32 v57, 0x7149f2ca, v56
	v_max_f32_e32 v56, 0xf149f2ca, v56
	v_cmp_ge_f32_e32 vcc, s57, v57
	v_sub_f32_e32 v57, 0xf149f2ca, v56
	s_cmp_eq_u64 vcc, exec
	v_mul_f32_e32 v57, 0x3dd53b94, v57
	s_cselect_b64 vcc, -1, 0
	v_exp_f32_e32 v57, v57
	v_cndmask_b32_e32 v156, v56, v219, vcc
	v_mul_f32_e32 v56, 0xbdd53b94, v156
	s_add_u32 s4, s14, 0x20000
	v_fmamk_f32 v36, v36, 0x3dd53b94, v56
	s_addc_u32 s5, s15, 0
	v_cndmask_b32_e64 v202, v57, 1.0, vcc
	v_fmamk_f32 v37, v37, 0x3dd53b94, v56
	v_mov_b32_e32 v57, v56
	v_exp_f32_e32 v221, v36
	s_add_u32 s18, s94, 0x20000
	v_add_co_u32_e32 v36, vcc, s42, v164
	v_fmamk_f32 v38, v38, 0x3dd53b94, v56
	v_fmamk_f32 v39, v39, 0x3dd53b94, v56
	v_fmac_f32_e32 v57, 0x3dd53b94, v51
	v_exp_f32_e32 v223, v37
	s_addc_u32 s19, s95, 0
	v_addc_co_u32_e32 v37, vcc, 0, v165, vcc
	v_pk_fma_f32 v[138:139], v[34:35], s[68:69], v[56:57] op_sel_hi:[1,0,0]
	v_pk_fma_f32 v[140:141], v[32:33], s[68:69], v[56:57] op_sel_hi:[1,0,0]
	v_pk_fma_f32 v[146:147], v[30:31], s[68:69], v[56:57] op_sel_hi:[1,0,0]
	v_pk_fma_f32 v[132:133], v[28:29], s[68:69], v[56:57] op_sel_hi:[1,0,0]
	v_pk_fma_f32 v[134:135], v[26:27], s[68:69], v[56:57] op_sel_hi:[1,0,0]
	v_pk_fma_f32 v[136:137], v[24:25], s[68:69], v[56:57] op_sel_hi:[1,0,0]
	v_pk_fma_f32 v[142:143], v[22:23], s[68:69], v[56:57] op_sel_hi:[1,0,0]
	v_pk_fma_f32 v[144:145], v[20:21], s[68:69], v[56:57] op_sel_hi:[1,0,0]
	v_exp_f32_e32 v153, v38
	v_exp_f32_e32 v222, v39
	global_load_dwordx4 v[20:23], v2, s[18:19]
	global_load_dwordx4 v[24:27], v162, s[18:19]
	global_load_dwordx4 v[28:31], v2, s[4:5]
	global_load_dwordx4 v[32:35], v162, s[4:5]
	v_fmamk_f32 v40, v40, 0x3dd53b94, v56
	global_load_dwordx4 v[36:39], v[36:37], off
	v_fmamk_f32 v41, v41, 0x3dd53b94, v56
	v_fmamk_f32 v42, v42, 0x3dd53b94, v56
	v_fmamk_f32 v43, v43, 0x3dd53b94, v56
	v_fmamk_f32 v44, v44, 0x3dd53b94, v56
	v_fmamk_f32 v45, v45, 0x3dd53b94, v56
	v_fmamk_f32 v46, v46, 0x3dd53b94, v56
	v_fmamk_f32 v47, v47, 0x3dd53b94, v56
	v_fmamk_f32 v48, v48, 0x3dd53b94, v56
	v_fmamk_f32 v49, v49, 0x3dd53b94, v56
	v_fmamk_f32 v50, v50, 0x3dd53b94, v56
	s_addk_i32 s6, 0x4000
	v_exp_f32_e32 v154, v40
	v_exp_f32_e32 v213, v41
	v_exp_f32_e32 v155, v42
	v_exp_f32_e32 v212, v43
	v_exp_f32_e32 v158, v44
	v_exp_f32_e32 v211, v45
	v_exp_f32_e32 v157, v46
	v_exp_f32_e32 v159, v47
	v_exp_f32_e32 v149, v48
	v_exp_f32_e32 v151, v49
	v_exp_f32_e32 v148, v50
	v_exp_f32_e32 v150, v57
	s_add_u32 s18, s94, 0x40000
	s_waitcnt vmcnt(0)
	s_addc_u32 s19, s95, 0
	s_waitcnt vmcnt(4)
	ds_write_b128 v176, v[20:23] offset:16384
	s_waitcnt vmcnt(3)
	ds_write_b128 v177, v[24:27] offset:16384
	s_waitcnt vmcnt(2)
	ds_write_b128 v180, v[28:31] offset:49152
	s_waitcnt vmcnt(1)
	ds_write_b128 v181, v[32:35] offset:49152
	v_add_u32_e32 v179, s6, v53
	s_waitcnt vmcnt(0)
	ds_write_b128 v204, v[36:39]
	s_add_u32 s20, s14, 0x40000
	v_mov_b64_e32 v[66:67], v[18:19]
	v_mov_b64_e32 v[50:51], v[18:19]
	v_mov_b64_e32 v[34:35], v[18:19]
	v_cmp_gt_u32_e64 s[4:5], 32, v168
	s_addc_u32 s21, s15, 0
	v_mov_b64_e32 v[64:65], v[16:17]
	v_mov_b64_e32 v[62:63], v[14:15]
	v_mov_b64_e32 v[60:61], v[12:13]
	v_mov_b64_e32 v[58:59], v[10:11]
	v_mov_b64_e32 v[56:57], v[8:9]
	v_mov_b64_e32 v[54:55], v[6:7]
	v_mov_b64_e32 v[52:53], v[4:5]
	v_mov_b64_e32 v[48:49], v[16:17]
	v_mov_b64_e32 v[46:47], v[14:15]
	v_mov_b64_e32 v[44:45], v[12:13]
	v_mov_b64_e32 v[42:43], v[10:11]
	v_mov_b64_e32 v[40:41], v[8:9]
	v_mov_b64_e32 v[38:39], v[6:7]
	v_mov_b64_e32 v[36:37], v[4:5]
	v_mov_b64_e32 v[32:33], v[16:17]
	v_mov_b64_e32 v[30:31], v[14:15]
	v_mov_b64_e32 v[28:29], v[12:13]
	v_mov_b64_e32 v[26:27], v[10:11]
	v_mov_b64_e32 v[24:25], v[8:9]
	v_mov_b64_e32 v[22:23], v[6:7]
	v_mov_b64_e32 v[20:21], v[4:5]
	s_waitcnt lgkmcnt(0)
	s_barrier
